# placement: F1G loop head at 0 mod 64 (FFN-F2 at 40, F3 at 56)
# speedup vs baseline: 1.0072x; 1.0072x over previous
.LBB0_957:
	s_add_u32 s41, s8, 0x13900000
	s_addc_u32 s42, s9, 0
	s_add_u32 s43, s8, 0x2600000
	s_mul_i32 s72, s14, 0xc000
	s_addc_u32 s44, s9, 0
	s_lshl_b64 s[14:15], s[72:73], 2
	s_add_u32 s8, s8, s14
	s_addc_u32 s9, s9, s15
	s_add_u32 s45, s8, 0x58000
	s_addc_u32 s46, s9, 0
	s_lshl_b32 s8, s13, 5
	s_and_b32 s13, s8, 0x60
	s_add_i32 m0, s19, 0x18000
	v_lshl_add_u64 v[6:7], v[6:7], 0, s[74:75]
	s_lshl_b32 s14, s12, 13
	s_lshl_b32 s15, s13, 7
	s_waitcnt vmcnt(2)
	s_barrier
	global_load_lds_dwordx4 v[6:7], off
	v_lshl_add_u64 v[4:5], v[4:5], 0, s[74:75]
	s_add_i32 m0, s19, 0x1a000
	s_add_i32 s47, s19, 0x8000
	s_add_i32 s48, s19, 0xa000
	global_load_lds_dwordx4 v[4:5], off
	v_lshl_add_u64 v[0:1], v[0:1], 0, s[74:75]
	s_mov_b32 m0, s47
	s_add_u32 s8, s30, 0x80080
	global_load_lds_dwordx4 v[0:1], off
	v_lshl_add_u64 v[0:1], v[2:3], 0, s[74:75]
	s_mov_b32 m0, s48
	s_addc_u32 s9, s31, 0
	global_load_lds_dwordx4 v[0:1], off
	s_add_i32 m0, s19, 0x1c000
	v_lshl_add_u64 v[0:1], s[8:9], 0, v[130:131]
	global_load_lds_dwordx4 v[0:1], off
	v_lshl_add_u64 v[0:1], s[8:9], 0, v[134:135]
	s_add_i32 m0, s19, 0x1e000
	s_cmpk_lt_u32 s10, 0x100
	global_load_lds_dwordx4 v[0:1], off
	v_lshrrev_b32_e32 v0, 1, v8
	v_and_b32_e32 v0, 24, v0
	v_and_b32_e32 v1, 15, v8
	v_lshlrev_b32_e32 v2, 1, v0
	v_lshl_or_b32 v136, s12, 6, v1
	v_lshl_or_b32 v1, v1, 6, v2
	v_lshlrev_b32_e32 v2, 2, v8
	v_and_b32_e32 v2, 32, v2
	v_bitop3_b32 v3, v1, s14, v2 bitop3:0xde
	v_bitop3_b32 v143, v1, s15, v2 bitop3:0xde
	v_lshlrev_b32_e32 v1, 15, v9
	v_and_b32_e32 v1, 0xffff0000, v1
	v_lshl_add_u32 v1, v10, 12, v1
	v_and_b32_e32 v2, 1, v9
	v_lshl_or_b32 v1, v2, 6, v1
	v_lshl_add_u32 v138, v11, 1, v1
	v_lshlrev_b32_e32 v1, 15, v12
	v_and_b32_e32 v1, 0xffff0000, v1
	s_waitcnt vmcnt(6)
	v_lshl_add_u32 v1, v13, 12, v1
	v_and_b32_e32 v2, 1, v12
	v_lshl_or_b32 v1, v2, 6, v1
	s_cselect_b64 s[8:9], -1, 0
	v_ashrrev_i32_e32 v137, 31, v136
	v_mov_b32_e32 v139, v177
	v_lshl_add_u32 v140, v14, 1, v1
	v_mov_b32_e32 v141, v177
	s_mov_b32 s49, 0
	v_add_u32_e32 v147, 0, v3
	s_lshl_b32 s10, s13, 1
	v_lshlrev_b32_e32 v176, 1, v0
	s_barrier
	s_branch .LBB0_960
	s_nop 0
	s_nop 0

.LBB0_1051:
	v_lshrrev_b32_e32 v15, 1, v14
	v_and_b32_e32 v15, 24, v15
	v_and_b32_e32 v221, 15, v14
	v_lshlrev_b32_e32 v16, 1, v15
	v_lshlrev_b32_e32 v14, 2, v14
	s_lshl_b32 s3, s3, 5
	s_lshl_b32 s60, s4, 6
	v_lshl_or_b32 v16, v221, 6, v16
	s_lshl_b32 s4, s4, 13
	v_and_b32_e32 v14, 32, v14
	s_and_b32 s3, s3, 0x60
	s_add_i32 m0, s42, 0x18000
	v_lshl_add_u64 v[6:7], v[6:7], 0, s[74:75]
	v_bitop3_b32 v17, v16, s4, v14 bitop3:0xde
	s_lshl_b32 s4, s3, 7
	s_waitcnt vmcnt(2)
	s_barrier
	global_load_lds_dwordx4 v[6:7], off
	v_lshl_add_u64 v[4:5], v[4:5], 0, s[74:75]
	s_add_i32 m0, s42, 0x1a000
	s_add_i32 s61, s42, 0x8000
	s_add_i32 s64, s42, 0xa000
	v_bitop3_b32 v222, v16, s4, v14 bitop3:0xde
	global_load_lds_dwordx4 v[4:5], off
	v_lshl_add_u64 v[0:1], v[0:1], 0, s[74:75]
	s_mov_b32 m0, s61
	s_add_u32 s4, s12, 0x80080
	global_load_lds_dwordx4 v[0:1], off
	v_lshl_add_u64 v[0:1], v[2:3], 0, s[74:75]
	s_mov_b32 m0, s64
	s_addc_u32 s5, s13, 0
	global_load_lds_dwordx4 v[0:1], off
	s_add_i32 m0, s42, 0x1c000
	v_lshl_add_u64 v[0:1], s[4:5], 0, v[176:177]
	global_load_lds_dwordx4 v[0:1], off
	v_lshl_add_u64 v[0:1], s[4:5], 0, v[178:179]
	s_add_i32 m0, s42, 0x1e000
	s_cmpk_lt_u32 s2, 0x100
	global_load_lds_dwordx4 v[0:1], off
	v_lshlrev_b32_e32 v0, 15, v12
	v_and_b32_e32 v0, 0xffff0000, v0
	v_lshl_add_u32 v0, v11, 12, v0
	v_and_b32_e32 v1, 1, v12
	v_lshl_or_b32 v0, v1, 6, v0
	v_lshl_add_u32 v184, v13, 1, v0
	v_lshlrev_b32_e32 v0, 15, v8
	s_cselect_b64 s[40:41], -1, 0
	s_add_u32 s46, s18, 0x5800
	v_and_b32_e32 v0, 0xffff0000, v0
	s_waitcnt vmcnt(6)
	s_addc_u32 s47, s19, 0
	v_lshl_add_u32 v0, v9, 12, v0
	v_and_b32_e32 v1, 1, v8
	s_add_u32 s48, s18, 0xb000
	v_lshl_or_b32 v0, v1, 6, v0
	v_readlane_b32 s14, v254, 39
	s_mov_b32 s65, 0
	v_cmp_eq_u32_e64 s[4:5], 0, v221
	v_cmp_eq_u32_e64 s[6:7], 15, v221
	s_addc_u32 s49, s19, 0
	v_or_b32_e32 v223, s3, v15
	v_mov_b32_e32 v185, v177
	v_lshl_add_u32 v186, v10, 1, v0
	v_mov_b32_e32 v187, v177
	v_add_u32_e32 v224, 0, v17
	v_readlane_b32 s2, v254, 38
	s_mov_b32 s3, s14
	s_barrier
	v_readlane_b32 s15, v254, 40
	s_branch .LBB0_1054
	s_nop 0
	s_nop 0
	s_nop 0
	s_nop 0
	s_nop 0
	s_nop 0
	s_nop 0
	s_nop 0
	s_nop 0
	s_nop 0
	s_nop 0
	s_nop 0
	s_nop 0
	s_nop 0
